# gemm_in q/k-norm tiles: z stores lane-transposed (coalesced) as in the generic path
# baseline (speedup 1.0000x reference)
; DI float xsum32(float x) { auto r = __builtin_amdgcn_permlane32_swap(__float_as_uint(x), __float_as_uint(x), false, false); return __uint_as_float(r[0]) + __uint_as_float(r[1]); }
; DI float xsum16(float x) { auto r = __builtin_amdgcn_permlane16_swap(__float_as_uint(x), __float_as_uint(x), false, false); return __uint_as_float(r[0]) + __uint_as_float(r[1]); }
; template <int EPI>
; DI void gemm_epilogue(const Params& p, int layer, f32x4 (&acc)[2][2][4][2], int brow, int bcol, int pn, int wr, int wc,
;                       int fr, int fq, char* smem, int ksplit = -1) {
;     ...
; #pragma unroll
;       for (int ai = 0; ai < 2; ++ai)
; #pragma unroll
;         for (int m = 0; m < 4; ++m)
; #pragma unroll
;           for (int bj = 0; bj < 2; ++bj) {
;             float s = 0.f;
; #pragma unroll
;             for (int n = 0; n < 2; ++n)
; #pragma unroll
;               for (int j = 0; j < 4; ++j) s += acc[ai][bj][m][n][j] * acc[ai][bj][m][n][j];
;             s = xsum16(s);
;             s = xsum32(s);
;             if (fq == 0) xch[(ai * 128 + wr * 64 + m * 16 + fr) * 8 + bj * 4 + wc] = s;
;           }
;       __syncthreads();
.LBB0_227:
	s_and_b64 vcc, exec, s[0:1]
	s_cbranch_vccz .LBB0_373
	v_and_b32_e32 v197, 63, v234
	v_lshrrev_b32_e32 v198, 2, v197
	v_and_b32_e32 v199, 15, v197
	v_sub_u32_e32 v199, v198, v199
	v_mul_i32_i24_e32 v199, 0x1c00, v199
	v_and_b32_e32 v195, 3, v197
	v_lshl_or_b32 v196, v195, 4, v198
	v_lshlrev_b32_e32 v196, 2, v196
	v_lshrrev_b32_e32 v198, 4, v197
	v_sub_u32_e32 v198, v195, v198
	v_lshl_add_u32 v194, v198, 4, v199
	v_ashrrev_i32_e32 v195, 31, v194
	v_mul_f32_e32 v130, v127, v127
	v_fmac_f32_e32 v130, v126, v126
	v_fmac_f32_e32 v130, v128, v128
	v_fmac_f32_e32 v130, v129, v129
	v_fmac_f32_e32 v130, v122, v122
	v_fmac_f32_e32 v130, v123, v123
	v_fmac_f32_e32 v130, v124, v124
	v_fmac_f32_e32 v130, v125, v125
	v_mov_b32_e32 v131, v130
	s_nop 1
	v_permlane16_swap_b32_e32 v130, v131
	v_add_f32_e32 v130, v130, v131
	v_lshlrev_b32_e32 v0, 5, v160
	v_mov_b32_e32 v131, v130
	v_cmp_eq_u32_e32 vcc, 0, v161
	s_nop 0
	v_permlane32_swap_b32_e32 v130, v131
	v_add_u32_e32 v0, s17, v0
	s_and_saveexec_b64 s[0:1], vcc
	v_add_f32_e32 v130, v130, v131
	ds_write_b32 v0, v130
	s_or_b64 exec, exec, s[0:1]
	v_mul_f32_e32 v130, v119, v119
	v_fmac_f32_e32 v130, v118, v118
	v_fmac_f32_e32 v130, v120, v120
	v_fmac_f32_e32 v130, v121, v121
	v_fmac_f32_e32 v130, v114, v114
	v_fmac_f32_e32 v130, v115, v115
	v_fmac_f32_e32 v130, v116, v116
	v_fmac_f32_e32 v130, v117, v117
	v_mov_b32_e32 v131, v130
	s_nop 1
	v_permlane16_swap_b32_e32 v130, v131
	v_add_f32_e32 v130, v130, v131
	v_mov_b32_e32 v131, v130
	s_nop 1
	v_permlane32_swap_b32_e32 v130, v131
	s_and_saveexec_b64 s[0:1], vcc
	v_add_f32_e32 v130, v130, v131
	ds_write_b32 v0, v130 offset:16
	s_or_b64 exec, exec, s[0:1]
	v_mul_f32_e32 v130, v111, v111
	v_fmac_f32_e32 v130, v110, v110
	v_fmac_f32_e32 v130, v112, v112
	v_fmac_f32_e32 v130, v113, v113
	v_fmac_f32_e32 v130, v106, v106
	v_fmac_f32_e32 v130, v107, v107
	v_fmac_f32_e32 v130, v108, v108
	v_fmac_f32_e32 v130, v109, v109
	v_mov_b32_e32 v131, v130
	s_nop 1
	v_permlane16_swap_b32_e32 v130, v131
	v_add_f32_e32 v130, v130, v131
	v_mov_b32_e32 v131, v130
	s_nop 1
	v_permlane32_swap_b32_e32 v130, v131
	s_and_saveexec_b64 s[0:1], vcc
	v_add_f32_e32 v130, v130, v131
	ds_write_b32 v0, v130 offset:512
	s_or_b64 exec, exec, s[0:1]
	v_mul_f32_e32 v130, v103, v103
	v_fmac_f32_e32 v130, v102, v102
	v_fmac_f32_e32 v130, v104, v104
	v_fmac_f32_e32 v130, v105, v105
	v_fmac_f32_e32 v130, v98, v98
	v_fmac_f32_e32 v130, v99, v99
	v_fmac_f32_e32 v130, v100, v100
	v_fmac_f32_e32 v130, v101, v101
	v_mov_b32_e32 v131, v130
	s_nop 1
	v_permlane16_swap_b32_e32 v130, v131
	v_add_f32_e32 v130, v130, v131
	v_mov_b32_e32 v131, v130
	s_nop 1
	v_permlane32_swap_b32_e32 v130, v131
	s_and_saveexec_b64 s[0:1], vcc
	v_add_f32_e32 v130, v130, v131
	ds_write_b32 v0, v130 offset:528
	s_or_b64 exec, exec, s[0:1]
	v_mul_f32_e32 v130, v95, v95
	v_fmac_f32_e32 v130, v94, v94
	v_fmac_f32_e32 v130, v96, v96
	v_fmac_f32_e32 v130, v97, v97
	v_fmac_f32_e32 v130, v90, v90
	v_fmac_f32_e32 v130, v91, v91
	v_fmac_f32_e32 v130, v92, v92
	v_fmac_f32_e32 v130, v93, v93
	v_mov_b32_e32 v131, v130
	s_nop 1
	v_permlane16_swap_b32_e32 v130, v131
	v_add_f32_e32 v130, v130, v131
	v_mov_b32_e32 v131, v130
	s_nop 1
	v_permlane32_swap_b32_e32 v130, v131
	s_and_saveexec_b64 s[0:1], vcc
	v_add_f32_e32 v130, v130, v131
	ds_write_b32 v0, v130 offset:1024
	s_or_b64 exec, exec, s[0:1]
	v_mul_f32_e32 v130, v87, v87
	v_fmac_f32_e32 v130, v86, v86
	v_fmac_f32_e32 v130, v88, v88
	v_fmac_f32_e32 v130, v89, v89
	v_fmac_f32_e32 v130, v82, v82
	v_fmac_f32_e32 v130, v83, v83
	v_fmac_f32_e32 v130, v84, v84
	v_fmac_f32_e32 v130, v85, v85
	v_mov_b32_e32 v131, v130
	s_nop 1
	v_permlane16_swap_b32_e32 v130, v131
	v_add_f32_e32 v130, v130, v131
	v_mov_b32_e32 v131, v130
	s_nop 1
	v_permlane32_swap_b32_e32 v130, v131
	s_and_saveexec_b64 s[0:1], vcc
	v_add_f32_e32 v130, v130, v131
	ds_write_b32 v0, v130 offset:1040
	s_or_b64 exec, exec, s[0:1]
	v_mul_f32_e32 v130, v79, v79
	v_fmac_f32_e32 v130, v78, v78
	v_fmac_f32_e32 v130, v80, v80
	v_fmac_f32_e32 v130, v81, v81
	v_fmac_f32_e32 v130, v74, v74
	v_fmac_f32_e32 v130, v75, v75
	v_fmac_f32_e32 v130, v76, v76
	v_fmac_f32_e32 v130, v77, v77
	v_mov_b32_e32 v131, v130
	s_nop 1
	v_permlane16_swap_b32_e32 v130, v131
	v_add_f32_e32 v130, v130, v131
	v_mov_b32_e32 v131, v130
	s_nop 1
	v_permlane32_swap_b32_e32 v130, v131
	s_and_saveexec_b64 s[0:1], vcc
	v_add_f32_e32 v130, v130, v131
	ds_write_b32 v0, v130 offset:1536
	s_or_b64 exec, exec, s[0:1]
	v_mul_f32_e32 v130, v71, v71
	v_fmac_f32_e32 v130, v70, v70
	v_fmac_f32_e32 v130, v72, v72
	v_fmac_f32_e32 v130, v73, v73
	v_fmac_f32_e32 v130, v66, v66
	v_fmac_f32_e32 v130, v67, v67
	v_fmac_f32_e32 v130, v68, v68
	v_fmac_f32_e32 v130, v69, v69
	v_mov_b32_e32 v131, v130
	s_nop 1
	v_permlane16_swap_b32_e32 v130, v131
	v_add_f32_e32 v130, v130, v131
	v_mov_b32_e32 v131, v130
	s_nop 1
	v_permlane32_swap_b32_e32 v130, v131
	s_and_saveexec_b64 s[0:1], vcc
	v_add_f32_e32 v130, v130, v131
	ds_write_b32 v0, v130 offset:1552
	s_or_b64 exec, exec, s[0:1]
	v_mul_f32_e32 v130, v63, v63
	v_fmac_f32_e32 v130, v62, v62
	v_fmac_f32_e32 v130, v64, v64
	v_fmac_f32_e32 v130, v65, v65
	v_fmac_f32_e32 v130, v58, v58
	v_fmac_f32_e32 v130, v59, v59
	v_fmac_f32_e32 v130, v60, v60
	v_fmac_f32_e32 v130, v61, v61
	v_mov_b32_e32 v131, v130
	s_nop 1
	v_permlane16_swap_b32_e32 v130, v131
	v_add_f32_e32 v130, v130, v131
	v_mov_b32_e32 v131, v130
	s_nop 1
	v_permlane32_swap_b32_e32 v130, v131
	s_and_saveexec_b64 s[0:1], vcc
	v_add_f32_e32 v130, v130, v131
	ds_write_b32 v0, v130 offset:4096
	s_or_b64 exec, exec, s[0:1]
	v_mul_f32_e32 v130, v55, v55
	v_fmac_f32_e32 v130, v54, v54
; DI float xsum32(float x) { auto r = __builtin_amdgcn_permlane32_swap(__float_as_uint(x), __float_as_uint(x), false, false); return __uint_as_float(r[0]) + __uint_as_float(r[1]); }
; DI float xsum16(float x) { auto r = __builtin_amdgcn_permlane16_swap(__float_as_uint(x), __float_as_uint(x), false, false); return __uint_as_float(r[0]) + __uint_as_float(r[1]); }
; template <int EPI>
; DI void gemm_epilogue(const Params& p, int layer, f32x4 (&acc)[2][2][4][2], int brow, int bcol, int pn, int wr, int wc,
;                       int fr, int fq, char* smem, int ksplit = -1) {
;     ...
;             float s = 0.f;
; #pragma unroll
;             for (int n = 0; n < 2; ++n)
; #pragma unroll
;               for (int j = 0; j < 4; ++j) s += acc[ai][bj][m][n][j] * acc[ai][bj][m][n][j];
;             s = xsum16(s);
;             s = xsum32(s);
;             if (fq == 0) xch[(ai * 128 + wr * 64 + m * 16 + fr) * 8 + bj * 4 + wc] = s;
;           }
;       __syncthreads();
;       const float* gq = (pn == 9 ? p.qn_g : p.kn_g) + layer * 64;
; #pragma unroll
;       for (int ai = 0; ai < 2; ++ai)
; #pragma unroll
;         for (int m = 0; m < 4; ++m) {
;           __builtin_amdgcn_sched_barrier(0);
;           const int rl = ai * 128 + wr * 64 + m * 16 + fr;
	v_fmac_f32_e32 v130, v56, v56
	v_fmac_f32_e32 v130, v57, v57
	v_fmac_f32_e32 v130, v50, v50
	v_fmac_f32_e32 v130, v51, v51
	v_fmac_f32_e32 v130, v52, v52
	v_fmac_f32_e32 v130, v53, v53
	v_mov_b32_e32 v131, v130
	s_nop 1
	v_permlane16_swap_b32_e32 v130, v131
	v_add_f32_e32 v130, v130, v131
	v_mov_b32_e32 v131, v130
	s_nop 1
	v_permlane32_swap_b32_e32 v130, v131
	s_and_saveexec_b64 s[0:1], vcc
	v_add_f32_e32 v130, v130, v131
	ds_write_b32 v0, v130 offset:4112
	s_or_b64 exec, exec, s[0:1]
	v_mul_f32_e32 v130, v47, v47
	v_fmac_f32_e32 v130, v46, v46
	v_fmac_f32_e32 v130, v48, v48
	v_fmac_f32_e32 v130, v49, v49
	v_fmac_f32_e32 v130, v42, v42
	v_fmac_f32_e32 v130, v43, v43
	v_fmac_f32_e32 v130, v44, v44
	v_fmac_f32_e32 v130, v45, v45
	v_mov_b32_e32 v131, v130
	s_nop 1
	v_permlane16_swap_b32_e32 v130, v131
	v_add_f32_e32 v130, v130, v131
	v_mov_b32_e32 v131, v130
	s_nop 1
	v_permlane32_swap_b32_e32 v130, v131
	s_and_saveexec_b64 s[0:1], vcc
	v_add_f32_e32 v130, v130, v131
	ds_write_b32 v0, v130 offset:4608
	s_or_b64 exec, exec, s[0:1]
	v_mul_f32_e32 v130, v39, v39
	v_fmac_f32_e32 v130, v38, v38
	v_fmac_f32_e32 v130, v40, v40
	v_fmac_f32_e32 v130, v41, v41
	v_fmac_f32_e32 v130, v34, v34
	v_fmac_f32_e32 v130, v35, v35
	v_fmac_f32_e32 v130, v36, v36
	v_fmac_f32_e32 v130, v37, v37
	v_mov_b32_e32 v131, v130
	s_nop 1
	v_permlane16_swap_b32_e32 v130, v131
	v_add_f32_e32 v130, v130, v131
	v_mov_b32_e32 v131, v130
	s_nop 1
	v_permlane32_swap_b32_e32 v130, v131
	s_and_saveexec_b64 s[0:1], vcc
	v_add_f32_e32 v130, v130, v131
	ds_write_b32 v0, v130 offset:4624
	s_or_b64 exec, exec, s[0:1]
	v_mul_f32_e32 v130, v31, v31
	v_fmac_f32_e32 v130, v30, v30
	v_fmac_f32_e32 v130, v32, v32
	v_fmac_f32_e32 v130, v33, v33
	v_fmac_f32_e32 v130, v26, v26
	v_fmac_f32_e32 v130, v27, v27
	v_fmac_f32_e32 v130, v28, v28
	v_fmac_f32_e32 v130, v29, v29
	v_mov_b32_e32 v131, v130
	s_nop 1
	v_permlane16_swap_b32_e32 v130, v131
	v_add_f32_e32 v130, v130, v131
	v_mov_b32_e32 v131, v130
	s_nop 1
	v_permlane32_swap_b32_e32 v130, v131
	s_and_saveexec_b64 s[0:1], vcc
	v_add_f32_e32 v130, v130, v131
	ds_write_b32 v0, v130 offset:5120
	s_or_b64 exec, exec, s[0:1]
	v_mul_f32_e32 v130, v23, v23
	v_fmac_f32_e32 v130, v22, v22
	v_fmac_f32_e32 v130, v24, v24
	v_fmac_f32_e32 v130, v25, v25
	v_fmac_f32_e32 v130, v18, v18
	v_fmac_f32_e32 v130, v19, v19
	v_fmac_f32_e32 v130, v20, v20
	v_fmac_f32_e32 v130, v21, v21
	v_mov_b32_e32 v131, v130
	s_nop 1
	v_permlane16_swap_b32_e32 v130, v131
	v_add_f32_e32 v130, v130, v131
	v_mov_b32_e32 v131, v130
	s_nop 1
	v_permlane32_swap_b32_e32 v130, v131
	s_and_saveexec_b64 s[0:1], vcc
	v_add_f32_e32 v130, v130, v131
	ds_write_b32 v0, v130 offset:5136
	s_or_b64 exec, exec, s[0:1]
	v_mul_f32_e32 v130, v15, v15
	v_fmac_f32_e32 v130, v14, v14
	v_fmac_f32_e32 v130, v16, v16
	v_fmac_f32_e32 v130, v17, v17
	v_fmac_f32_e32 v130, v10, v10
	v_fmac_f32_e32 v130, v11, v11
	v_fmac_f32_e32 v130, v12, v12
	v_fmac_f32_e32 v130, v13, v13
	v_mov_b32_e32 v131, v130
	s_nop 1
	v_permlane16_swap_b32_e32 v130, v131
	v_add_f32_e32 v130, v130, v131
	v_mov_b32_e32 v131, v130
	s_nop 1
	v_permlane32_swap_b32_e32 v130, v131
	s_and_saveexec_b64 s[0:1], vcc
	v_add_f32_e32 v130, v130, v131
	ds_write_b32 v0, v130 offset:5632
	s_or_b64 exec, exec, s[0:1]
	v_mul_f32_e32 v130, v7, v7
	v_fmac_f32_e32 v130, v6, v6
	v_fmac_f32_e32 v130, v8, v8
	v_fmac_f32_e32 v130, v9, v9
	v_fmac_f32_e32 v130, v2, v2
	v_fmac_f32_e32 v130, v3, v3
	v_fmac_f32_e32 v130, v4, v4
	v_fmac_f32_e32 v130, v5, v5
	v_mov_b32_e32 v131, v130
	s_nop 1
	v_permlane16_swap_b32_e32 v130, v131
	v_add_f32_e32 v130, v130, v131
	v_mov_b32_e32 v131, v130
	s_nop 1
	v_permlane32_swap_b32_e32 v130, v131
	s_and_saveexec_b64 s[0:1], vcc
	v_add_f32_e32 v130, v130, v131
	ds_write_b32 v0, v130 offset:5648
	s_or_b64 exec, exec, s[0:1]
	s_cmpk_lt_u32 s23, 0x80
	s_cselect_b64 s[2:3], -1, 0
	s_cmp_eq_u32 s24, 9
	s_cselect_b64 s[0:1], -1, 0
	s_and_b64 s[4:5], s[0:1], exec
	v_readlane_b32 s60, v252, 32
	v_readlane_b32 s4, v255, 1
	v_readlane_b32 s70, v252, 42
	v_readlane_b32 s71, v252, 43
	v_readlane_b32 s72, v252, 44
	v_readlane_b32 s73, v252, 45
	v_readlane_b32 s5, v255, 2
	s_cselect_b32 s24, s71, s73
	s_cselect_b32 s26, s70, s72
	s_lshl_b64 s[4:5], s[4:5], 2
	s_add_u32 s4, s26, s4
	v_lshlrev_b32_e32 v156, 3, v161
	s_addc_u32 s5, s24, s5
	s_add_i32 s24, 0, 0x20000
	v_or_b32_e32 v154, s14, v160
	v_or_b32_e32 v140, s18, v156
	v_readlane_b32 s61, v252, 33
	v_readlane_b32 s62, v252, 34
	v_readlane_b32 s63, v252, 35
	v_readlane_b32 s64, v252, 36
	v_readlane_b32 s65, v252, 37
	v_readlane_b32 s66, v252, 38
	v_readlane_b32 s67, v252, 39
	v_readlane_b32 s68, v252, 40
	v_readlane_b32 s69, v252, 41
	v_readlane_b32 s74, v252, 46
	v_readlane_b32 s75, v252, 47
	s_cmpk_gt_u32 s23, 0x7f
	s_waitcnt vmcnt(0) lgkmcnt(0)
	s_barrier
; template <int EPI>
; DI void gemm_epilogue(const Params& p, int layer, f32x4 (&acc)[2][2][4][2], int brow, int bcol, int pn, int wr, int wc,
;                       int fr, int fq, char* smem, int ksplit = -1) {
;     ...
;           const int rl = ai * 128 + wr * 64 + m * 16 + fr;
;           const int row = brow + rl;
;           const int spos = row & (SEQ - 1);
; #pragma unroll
;           for (int bj = 0; bj < 2; ++bj) {
;             const bool normed = (pn == 9) || (bj == 0);
;             float rs = 1.f;
;             if (normed) {
;               float tot = xch[rl * 8 + bj * 4 + wc] + xch[rl * 8 + bj * 4 + (wc ^ 1)];
;               rs = __builtin_amdgcn_rsqf(tot * (1.f / 64.f) + EPSN);
;             }
;             u32x4 o;
; #pragma unroll
;             for (int n = 0; n < 2; ++n) {
;               const int cih = (wc & 1) * 32 + fq * 8 + n * 4;
;               f32x4 v = acc[ai][bj][m][n];
;               if (normed) {
;                 f32x4 g = *(const f32x4*)(gq + cih);
;                 v = v * rs * g;
;                 if (latent) {
;                   const float2 cs = *(const float2*)(p.ropec + spos * 32 + (cih >> 1));
;                   const float2 sn = *(const float2*)(p.ropes + spos * 32 + (cih >> 1));
;                   f32x4 r;
;                   r[0] = v[0] * cs.x - v[1] * sn.x;
;                   r[1] = v[0] * sn.x + v[1] * cs.x;
;                   r[2] = v[2] * cs.y - v[3] * sn.y;
;                   r[3] = v[2] * sn.y + v[3] * cs.y;
;                   v = r;
;                 }
	v_add_u32_e32 v155, s22, v154
	v_lshlrev_b32_e32 v0, 7, v155
	v_readlane_b32 s60, v254, 45
	v_and_b32_e32 v0, 0x3e780, v0
	v_readlane_b32 s66, v254, 51
	v_readlane_b32 s67, v254, 52
	v_readlane_b32 s68, v254, 53
	v_readlane_b32 s69, v254, 54
	v_lshl_add_u64 v[132:133], s[66:67], 0, v[0:1]
	v_lshlrev_b32_e32 v134, 3, v154
	v_lshl_add_u64 v[130:131], s[68:69], 0, v[0:1]
	v_lshlrev_b32_e32 v182, 1, v140
	v_mov_b32_e32 v183, 0
	v_lshl_add_u64 v[184:185], v[132:133], 0, v[182:183]
	global_load_dwordx4 v[186:189], v[184:185], off
	v_lshl_add_u64 v[184:185], v[130:131], 0, v[182:183]
	global_load_dwordx4 v[190:193], v[184:185], off
	v_lshlrev_b32_e32 v0, 2, v140
	global_load_dwordx4 v[162:165], v0, s[4:5]
	global_load_dwordx4 v[168:171], v0, s[4:5]
	global_load_dwordx4 v[178:181], v0, s[4:5] offset:16
	v_lshlrev_b32_e32 v182, 1, v140
	v_mov_b32_e32 v183, 0
	v_or_b32_e32 v160, s13, v134
	v_bitop3_b32 v134, v134, 1, s13 bitop3:0x36
	v_lshl_add_u32 v157, v160, 2, s24
	v_lshl_add_u32 v134, v134, 2, s24
	ds_read_b32 v135, v157
	ds_read_b32 v134, v134
	v_readlane_b32 s61, v254, 46
	v_readlane_b32 s62, v254, 47
	v_readlane_b32 s63, v254, 48
	v_readlane_b32 s64, v254, 49
	s_waitcnt lgkmcnt(0)
	v_add_f32_e32 v134, v135, v134
	v_fmamk_f32 v134, v134, 0x3c800000, v236
	v_rsq_f32_e32 v136, v134
	v_readlane_b32 s65, v254, 50
	v_readlane_b32 s70, v254, 55
	v_readlane_b32 s71, v254, 56
	v_pk_mul_f32 v[126:127], v[126:127], v[136:137] op_sel_hi:[1,0]
	v_pk_mul_f32 v[128:129], v[128:129], v[136:137] op_sel_hi:[1,0]
	v_readlane_b32 s72, v254, 57
	v_readlane_b32 s73, v254, 58
	v_readlane_b32 s74, v254, 59
	v_readlane_b32 s75, v254, 60
	s_waitcnt vmcnt(0)
	v_pk_mul_f32 v[134:135], v[164:165], v[128:129]
	v_pk_mul_f32 v[128:129], v[162:163], v[126:127]
	s_cbranch_scc1 .LBB0_262
	v_lshlrev_b32_e32 v126, 1, v140
	v_mov_b32_e32 v127, v1
	v_lshl_add_u64 v[138:139], v[132:133], 0, v[126:127]
	v_lshl_add_u64 v[126:127], v[130:131], 0, v[126:127]
	v_mov_b64_e32 v[126:127], v[190:191]
	v_pk_mul_f32 v[162:163], v[128:129], v[126:127] op_sel:[1,0] op_sel_hi:[0,0]
	v_mov_b64_e32 v[138:139], v[186:187]
	v_pk_mul_f32 v[164:165], v[128:129], v[138:139]
	v_pk_fma_f32 v[128:129], v[128:129], v[138:139], v[162:163] op_sel_hi:[1,0,1]
	v_mov_b32_e32 v126, v139
	v_mul_f32_e32 v128, v135, v127
	v_pk_fma_f32 v[166:167], v[134:135], v[126:127], v[128:129] op_sel_hi:[1,1,0] neg_lo:[0,0,1] neg_hi:[0,0,1]
	v_mov_b32_e32 v138, v127
	v_mul_f32_e32 v126, v135, v139
	v_pk_fma_f32 v[126:127], v[134:135], v[138:139], v[126:127] op_sel_hi:[1,1,0]
	v_sub_f32_e32 v128, v164, v162
	v_mov_b32_e32 v134, v166
	v_mov_b32_e32 v135, v126

; template <int EPI>
; DI void gemm_epilogue(const Params& p, int layer, f32x4 (&acc)[2][2][4][2], int brow, int bcol, int pn, int wr, int wc,
;                       int fr, int fq, char* smem, int ksplit = -1) {
;     ...
;                 if (pn == 9) v = v * 0.125f;
;               }
;               o[2 * n] = pk_bf16(v[0], v[1]);
;               o[2 * n + 1] = pk_bf16(v[2], v[3]);
;             }
;             *(u32x4*)(Z + (size_t)row * ZW + bcol + bj * 128 + wc * 32 + fq * 8) = o;
.LBB0_264:
	v_pk_mul_f32 v[124:125], v[134:135], s[54:55] op_sel_hi:[1,0]
	s_lshl_b32 s2, s25, 1
	v_pk_mul_f32 v[122:123], v[128:129], s[54:55] op_sel_hi:[1,0]
	v_cndmask_b32_e64 v0, v135, v125, s[0:1]
	v_cndmask_b32_e64 v124, v134, v124, s[0:1]
	s_add_u32 s2, s19, s2
	v_cndmask_b32_e64 v123, v129, v123, s[0:1]
	v_cndmask_b32_e64 v122, v128, v122, s[0:1]
	v_cvt_pk_bf16_f32 v135, v124, v0
	s_addc_u32 s3, s20, 0
	v_lshlrev_b32_e32 v0, 1, v156
	v_pk_mul_f32 v[162:163], v[138:139], s[54:55] op_sel_hi:[1,0]
	v_cvt_pk_bf16_f32 v134, v122, v123
	v_lshl_add_u64 v[122:123], s[2:3], 0, v[0:1]
	v_pk_mul_f32 v[128:129], v[136:137], s[54:55] op_sel_hi:[1,0]
	v_cndmask_b32_e64 v0, v139, v163, s[0:1]
	v_cndmask_b32_e64 v138, v138, v162, s[0:1]
	v_cndmask_b32_e64 v129, v137, v129, s[0:1]
	v_cndmask_b32_e64 v128, v136, v128, s[0:1]
	v_cvt_pk_bf16_f32 v137, v138, v0
	v_cndmask_b32_e64 v0, 0, 1, s[0:1]
	v_mad_i64_i32 v[124:125], s[2:3], v155, s79, v[122:123]
	v_cvt_pk_bf16_f32 v136, v128, v129
	v_cmp_ne_u32_e64 s[42:43], 1, v0
	s_andn2_b64 vcc, exec, s[0:1]
	v_mov_b32_e32 v128, 1.0
	v_lshl_add_u64 v[124:125], v[124:125], 0, v[194:195]
	ds_bpermute_b32 v134, v196, v134
	ds_bpermute_b32 v135, v196, v135
	ds_bpermute_b32 v136, v196, v136
	ds_bpermute_b32 v137, v196, v137
	s_waitcnt lgkmcnt(0)
	global_store_dwordx4 v[124:125], v[134:137], off
	s_cbranch_vccnz .LBB0_267
	v_xor_b32_e32 v0, 5, v160
	v_lshl_add_u32 v0, v0, 2, 0
	v_add_u32_e32 v0, 0x20000, v0
	ds_read_b32 v128, v157 offset:16
	ds_read_b32 v0, v0
	s_waitcnt lgkmcnt(0)
	v_add_f32_e32 v0, v128, v0
	v_fmamk_f32 v0, v0, 0x3c800000, v236
	v_rsq_f32_e32 v128, v0
	s_and_b64 vcc, exec, s[42:43]
	v_mov_b32_e32 v129, v128
	s_cbranch_vccz .LBB0_268

; template <int EPI>
; DI void gemm_epilogue(const Params& p, int layer, f32x4 (&acc)[2][2][4][2], int brow, int bcol, int pn, int wr, int wc,
;                       int fr, int fq, char* smem, int ksplit = -1) {
;     ...
;             u32x4 o;
; #pragma unroll
;             for (int n = 0; n < 2; ++n) {
;               const int cih = (wc & 1) * 32 + fq * 8 + n * 4;
;               f32x4 v = acc[ai][bj][m][n];
;               if (normed) {
;                 f32x4 g = *(const f32x4*)(gq + cih);
;                 v = v * rs * g;
;                 if (latent) {
;                   const float2 cs = *(const float2*)(p.ropec + spos * 32 + (cih >> 1));
;                   const float2 sn = *(const float2*)(p.ropes + spos * 32 + (cih >> 1));
;                   f32x4 r;
;                   r[0] = v[0] * cs.x - v[1] * sn.x;
;                   r[1] = v[0] * sn.x + v[1] * cs.x;
;                   r[2] = v[2] * cs.y - v[3] * sn.y;
;                   r[3] = v[2] * sn.y + v[3] * cs.y;
;                   v = r;
;                 }
;                 if (pn == 9) v = v * 0.125f;
;               }
;               o[2 * n] = pk_bf16(v[0], v[1]);
;               o[2 * n + 1] = pk_bf16(v[2], v[3]);
;             }
;             *(u32x4*)(Z + (size_t)row * ZW + bcol + bj * 128 + wc * 32 + fq * 8) = o;
.LBB0_274:
	v_cvt_pk_bf16_f32 v118, v118, v119
	v_cvt_pk_bf16_f32 v119, v120, v121
	v_cvt_pk_bf16_f32 v120, v114, v115
	v_cvt_pk_bf16_f32 v121, v116, v117
	ds_bpermute_b32 v118, v196, v118
	ds_bpermute_b32 v119, v196, v119
	ds_bpermute_b32 v120, v196, v120
	ds_bpermute_b32 v121, v196, v121
	s_waitcnt lgkmcnt(0)
	global_store_dwordx4 v[124:125], v[118:121], off offset:256
	v_mov_b64_e32 v[128:129], v[168:169]
	v_mov_b64_e32 v[130:131], v[170:171]
	v_or_b32_e32 v0, 16, v154
	v_lshlrev_b32_e32 v114, 3, v0
	v_or_b32_e32 v121, s13, v114
	v_bitop3_b32 v114, v114, 1, s13 bitop3:0x36
	v_lshl_add_u32 v120, v121, 2, s24
	v_lshl_add_u32 v114, v114, 2, s24
	ds_read_b32 v115, v120
	ds_read_b32 v114, v114
	v_add_u32_e32 v124, s22, v0
	v_lshlrev_b32_e32 v0, 7, v124
	v_readlane_b32 s60, v254, 45
	v_and_b32_e32 v0, 0x3ef80, v0
	s_waitcnt lgkmcnt(0)
	v_add_f32_e32 v114, v115, v114
	v_fmamk_f32 v114, v114, 0x3c800000, v236
	v_rsq_f32_e32 v118, v114
	v_readlane_b32 s66, v254, 51
	v_readlane_b32 s67, v254, 52
	v_readlane_b32 s68, v254, 53
	v_readlane_b32 s69, v254, 54
	v_pk_mul_f32 v[110:111], v[110:111], v[118:119] op_sel_hi:[1,0]
	v_pk_mul_f32 v[112:113], v[112:113], v[118:119] op_sel_hi:[1,0]
	s_and_b64 vcc, exec, s[40:41]
	v_lshl_add_u64 v[116:117], s[66:67], 0, v[0:1]
	v_lshl_add_u64 v[114:115], s[68:69], 0, v[0:1]
	v_lshl_add_u64 v[184:185], v[116:117], 0, v[182:183]
	global_load_dwordx4 v[186:189], v[184:185], off
	v_lshl_add_u64 v[184:185], v[114:115], 0, v[182:183]
	global_load_dwordx4 v[190:193], v[184:185], off
	v_readlane_b32 s61, v254, 46
	v_readlane_b32 s62, v254, 47
	v_readlane_b32 s63, v254, 48
	v_readlane_b32 s64, v254, 49
	v_readlane_b32 s65, v254, 50
	v_readlane_b32 s70, v254, 55
	v_readlane_b32 s71, v254, 56
	v_readlane_b32 s72, v254, 57
	v_readlane_b32 s73, v254, 58
	v_readlane_b32 s74, v254, 59
	v_readlane_b32 s75, v254, 60
	v_pk_mul_f32 v[112:113], v[130:131], v[112:113]
	v_pk_mul_f32 v[110:111], v[128:129], v[110:111]
	s_cbranch_vccnz .LBB0_276
	v_lshlrev_b32_e32 v0, 1, v140
	v_lshl_add_u64 v[128:129], v[116:117], 0, v[0:1]
	v_lshl_add_u64 v[130:131], v[114:115], 0, v[0:1]
	s_waitcnt vmcnt(0)
	v_mov_b64_e32 v[128:129], v[186:187]
	v_pk_mul_f32 v[134:135], v[110:111], v[128:129]
	v_mov_b64_e32 v[130:131], v[190:191]
	v_pk_mul_f32 v[132:133], v[110:111], v[130:131] op_sel:[1,0] op_sel_hi:[0,0]
	v_mov_b32_e32 v130, v129
	v_mul_f32_e32 v0, v113, v131
	v_pk_fma_f32 v[110:111], v[110:111], v[128:129], v[132:133] op_sel_hi:[1,0,1]
	v_pk_fma_f32 v[136:137], v[112:113], v[130:131], v[0:1] op_sel_hi:[1,1,0] neg_lo:[0,0,1] neg_hi:[0,0,1]
	v_mov_b32_e32 v128, v131
	v_mul_f32_e32 v0, v113, v129
	v_pk_fma_f32 v[128:129], v[112:113], v[128:129], v[0:1] op_sel_hi:[1,1,0]
	v_sub_f32_e32 v110, v134, v132
	v_mov_b32_e32 v112, v136
	v_mov_b32_e32 v113, v128

; template <int EPI>
; DI void gemm_epilogue(const Params& p, int layer, f32x4 (&acc)[2][2][4][2], int brow, int bcol, int pn, int wr, int wc,
;                       int fr, int fq, char* smem, int ksplit = -1) {
;     ...
;                 if (pn == 9) v = v * 0.125f;
;               }
;               o[2 * n] = pk_bf16(v[0], v[1]);
;               o[2 * n + 1] = pk_bf16(v[2], v[3]);
;             }
;             *(u32x4*)(Z + (size_t)row * ZW + bcol + bj * 128 + wc * 32 + fq * 8) = o;
.LBB0_278:
	v_pk_mul_f32 v[106:107], v[110:111], s[54:55] op_sel_hi:[1,0]
	v_pk_mul_f32 v[128:129], v[112:113], s[54:55] op_sel_hi:[1,0]
	v_cndmask_b32_e64 v107, v111, v107, s[0:1]
	v_cndmask_b32_e64 v0, v113, v129, s[0:1]
	v_cndmask_b32_e64 v112, v112, v128, s[0:1]
	v_cndmask_b32_e64 v106, v110, v106, s[0:1]
	v_cvt_pk_bf16_f32 v110, v106, v107
	v_cvt_pk_bf16_f32 v111, v112, v0
	v_mad_i64_i32 v[106:107], s[2:3], v124, s79, v[122:123]
	v_pk_mul_f32 v[112:113], v[108:109], s[54:55] op_sel_hi:[1,0]
	v_pk_mul_f32 v[124:125], v[118:119], s[54:55] op_sel_hi:[1,0]
	v_cndmask_b32_e64 v109, v109, v113, s[0:1]
	v_cndmask_b32_e64 v0, v119, v125, s[0:1]
	v_cndmask_b32_e64 v118, v118, v124, s[0:1]
	v_cndmask_b32_e64 v108, v108, v112, s[0:1]
	v_cvt_pk_bf16_f32 v112, v108, v109
	v_cvt_pk_bf16_f32 v113, v118, v0
	s_and_b64 vcc, exec, s[42:43]
	v_mov_b32_e32 v108, 1.0
	v_lshl_add_u64 v[106:107], v[106:107], 0, v[194:195]
	ds_bpermute_b32 v110, v196, v110
	ds_bpermute_b32 v111, v196, v111
	ds_bpermute_b32 v112, v196, v112
	ds_bpermute_b32 v113, v196, v113
	s_waitcnt lgkmcnt(0)
	global_store_dwordx4 v[106:107], v[110:113], off
	s_cbranch_vccnz .LBB0_281
	v_xor_b32_e32 v0, 5, v121
	v_lshl_add_u32 v0, v0, 2, 0
	v_add_u32_e32 v0, 0x20000, v0
	ds_read_b32 v108, v120 offset:16
	ds_read_b32 v0, v0
	s_waitcnt lgkmcnt(0)
	v_add_f32_e32 v0, v108, v0
	v_fmamk_f32 v0, v0, 0x3c800000, v236
	v_rsq_f32_e32 v108, v0
	s_and_b64 vcc, exec, s[42:43]
	v_mov_b32_e32 v109, v108
	s_cbranch_vccz .LBB0_282

; template <int EPI>
; DI void gemm_epilogue(const Params& p, int layer, f32x4 (&acc)[2][2][4][2], int brow, int bcol, int pn, int wr, int wc,
;                       int fr, int fq, char* smem, int ksplit = -1) {
;     ...
;             u32x4 o;
; #pragma unroll
;             for (int n = 0; n < 2; ++n) {
;               const int cih = (wc & 1) * 32 + fq * 8 + n * 4;
;               f32x4 v = acc[ai][bj][m][n];
;               if (normed) {
;                 f32x4 g = *(const f32x4*)(gq + cih);
;                 v = v * rs * g;
;                 if (latent) {
;                   const float2 cs = *(const float2*)(p.ropec + spos * 32 + (cih >> 1));
;                   const float2 sn = *(const float2*)(p.ropes + spos * 32 + (cih >> 1));
;                   f32x4 r;
;                   r[0] = v[0] * cs.x - v[1] * sn.x;
;                   r[1] = v[0] * sn.x + v[1] * cs.x;
;                   r[2] = v[2] * cs.y - v[3] * sn.y;
;                   r[3] = v[2] * sn.y + v[3] * cs.y;
;                   v = r;
;                 }
;                 if (pn == 9) v = v * 0.125f;
;               }
;               o[2 * n] = pk_bf16(v[0], v[1]);
;               o[2 * n + 1] = pk_bf16(v[2], v[3]);
;             }
;             *(u32x4*)(Z + (size_t)row * ZW + bcol + bj * 128 + wc * 32 + fq * 8) = o;
.LBB0_288:
	v_cvt_pk_bf16_f32 v102, v102, v103
	v_cvt_pk_bf16_f32 v103, v104, v105
	v_cvt_pk_bf16_f32 v104, v98, v99
	v_cvt_pk_bf16_f32 v105, v100, v101
	ds_bpermute_b32 v102, v196, v102
	ds_bpermute_b32 v103, v196, v103
	ds_bpermute_b32 v104, v196, v104
	ds_bpermute_b32 v105, v196, v105
	s_waitcnt lgkmcnt(0)
	global_store_dwordx4 v[106:107], v[102:105], off offset:256
	v_mov_b64_e32 v[108:109], v[168:169]
	v_mov_b64_e32 v[110:111], v[170:171]
	v_or_b32_e32 v0, 32, v154
	v_lshlrev_b32_e32 v98, 3, v0
	v_or_b32_e32 v105, s13, v98
	v_bitop3_b32 v98, v98, 1, s13 bitop3:0x36
	v_lshl_add_u32 v104, v105, 2, s24
	v_lshl_add_u32 v98, v98, 2, s24
	ds_read_b32 v99, v104
	ds_read_b32 v98, v98
	v_add_u32_e32 v106, s22, v0
	v_lshlrev_b32_e32 v0, 7, v106
	v_readlane_b32 s60, v254, 45
	v_and_b32_e32 v0, 0x3f780, v0
	s_waitcnt lgkmcnt(0)
	v_add_f32_e32 v98, v99, v98
	v_fmamk_f32 v98, v98, 0x3c800000, v236
	v_rsq_f32_e32 v102, v98
	v_readlane_b32 s66, v254, 51
	v_readlane_b32 s67, v254, 52
	v_readlane_b32 s68, v254, 53
	v_readlane_b32 s69, v254, 54
	v_pk_mul_f32 v[94:95], v[94:95], v[102:103] op_sel_hi:[1,0]
	v_pk_mul_f32 v[96:97], v[96:97], v[102:103] op_sel_hi:[1,0]
	s_and_b64 vcc, exec, s[40:41]
	v_lshl_add_u64 v[100:101], s[66:67], 0, v[0:1]
	v_lshl_add_u64 v[98:99], s[68:69], 0, v[0:1]
	v_lshl_add_u64 v[184:185], v[100:101], 0, v[182:183]
	global_load_dwordx4 v[186:189], v[184:185], off
	v_lshl_add_u64 v[184:185], v[98:99], 0, v[182:183]
	global_load_dwordx4 v[190:193], v[184:185], off
	v_readlane_b32 s61, v254, 46
	v_readlane_b32 s62, v254, 47
	v_readlane_b32 s63, v254, 48
	v_readlane_b32 s64, v254, 49
	v_readlane_b32 s65, v254, 50
	v_readlane_b32 s70, v254, 55
	v_readlane_b32 s71, v254, 56
	v_readlane_b32 s72, v254, 57
	v_readlane_b32 s73, v254, 58
	v_readlane_b32 s74, v254, 59
	v_readlane_b32 s75, v254, 60
	v_pk_mul_f32 v[96:97], v[110:111], v[96:97]
	v_pk_mul_f32 v[94:95], v[108:109], v[94:95]
	s_cbranch_vccnz .LBB0_290
	v_lshlrev_b32_e32 v0, 1, v140
	v_lshl_add_u64 v[108:109], v[100:101], 0, v[0:1]
	v_lshl_add_u64 v[110:111], v[98:99], 0, v[0:1]
	s_waitcnt vmcnt(0)
	v_mov_b64_e32 v[108:109], v[186:187]
	v_pk_mul_f32 v[114:115], v[94:95], v[108:109]
	v_mov_b64_e32 v[110:111], v[190:191]
	v_pk_mul_f32 v[112:113], v[94:95], v[110:111] op_sel:[1,0] op_sel_hi:[0,0]
	v_mov_b32_e32 v110, v109
	v_mul_f32_e32 v0, v97, v111
	v_pk_fma_f32 v[94:95], v[94:95], v[108:109], v[112:113] op_sel_hi:[1,0,1]
	v_pk_fma_f32 v[116:117], v[96:97], v[110:111], v[0:1] op_sel_hi:[1,1,0] neg_lo:[0,0,1] neg_hi:[0,0,1]
	v_mov_b32_e32 v108, v111
	v_mul_f32_e32 v0, v97, v109
	v_pk_fma_f32 v[108:109], v[96:97], v[108:109], v[0:1] op_sel_hi:[1,1,0]
	v_sub_f32_e32 v94, v114, v112
	v_mov_b32_e32 v96, v116
	v_mov_b32_e32 v97, v108

; template <int EPI>
; DI void gemm_epilogue(const Params& p, int layer, f32x4 (&acc)[2][2][4][2], int brow, int bcol, int pn, int wr, int wc,
;                       int fr, int fq, char* smem, int ksplit = -1) {
;     ...
;                 if (pn == 9) v = v * 0.125f;
;               }
;               o[2 * n] = pk_bf16(v[0], v[1]);
;               o[2 * n + 1] = pk_bf16(v[2], v[3]);
;             }
;             *(u32x4*)(Z + (size_t)row * ZW + bcol + bj * 128 + wc * 32 + fq * 8) = o;
.LBB0_292:
	v_pk_mul_f32 v[90:91], v[94:95], s[54:55] op_sel_hi:[1,0]
	v_pk_mul_f32 v[108:109], v[96:97], s[54:55] op_sel_hi:[1,0]
	v_cndmask_b32_e64 v91, v95, v91, s[0:1]
	v_cndmask_b32_e64 v0, v97, v109, s[0:1]
	v_cndmask_b32_e64 v96, v96, v108, s[0:1]
	v_cndmask_b32_e64 v90, v94, v90, s[0:1]
	v_cvt_pk_bf16_f32 v94, v90, v91
	v_cvt_pk_bf16_f32 v95, v96, v0
	v_mad_i64_i32 v[90:91], s[2:3], v106, s79, v[122:123]
	v_pk_mul_f32 v[96:97], v[92:93], s[54:55] op_sel_hi:[1,0]
	v_pk_mul_f32 v[106:107], v[102:103], s[54:55] op_sel_hi:[1,0]
	v_cndmask_b32_e64 v93, v93, v97, s[0:1]
	v_cndmask_b32_e64 v0, v103, v107, s[0:1]
	v_cndmask_b32_e64 v102, v102, v106, s[0:1]
	v_cndmask_b32_e64 v92, v92, v96, s[0:1]
	v_cvt_pk_bf16_f32 v96, v92, v93
	v_cvt_pk_bf16_f32 v97, v102, v0
	s_and_b64 vcc, exec, s[42:43]
	v_mov_b32_e32 v92, 1.0
	v_lshl_add_u64 v[90:91], v[90:91], 0, v[194:195]
	ds_bpermute_b32 v94, v196, v94
	ds_bpermute_b32 v95, v196, v95
	ds_bpermute_b32 v96, v196, v96
	ds_bpermute_b32 v97, v196, v97
	s_waitcnt lgkmcnt(0)
	global_store_dwordx4 v[90:91], v[94:97], off
	s_cbranch_vccnz .LBB0_295
	v_xor_b32_e32 v0, 5, v105
	v_lshl_add_u32 v0, v0, 2, 0
	v_add_u32_e32 v0, 0x20000, v0
	ds_read_b32 v92, v104 offset:16
	ds_read_b32 v0, v0
	s_waitcnt lgkmcnt(0)
	v_add_f32_e32 v0, v92, v0
	v_fmamk_f32 v0, v0, 0x3c800000, v236
	v_rsq_f32_e32 v92, v0
	s_and_b64 vcc, exec, s[42:43]
	v_mov_b32_e32 v93, v92
	s_cbranch_vccz .LBB0_296

; template <int EPI>
; DI void gemm_epilogue(const Params& p, int layer, f32x4 (&acc)[2][2][4][2], int brow, int bcol, int pn, int wr, int wc,
;                       int fr, int fq, char* smem, int ksplit = -1) {
;     ...
;             u32x4 o;
; #pragma unroll
;             for (int n = 0; n < 2; ++n) {
;               const int cih = (wc & 1) * 32 + fq * 8 + n * 4;
;               f32x4 v = acc[ai][bj][m][n];
;               if (normed) {
;                 f32x4 g = *(const f32x4*)(gq + cih);
;                 v = v * rs * g;
;                 if (latent) {
;                   const float2 cs = *(const float2*)(p.ropec + spos * 32 + (cih >> 1));
;                   const float2 sn = *(const float2*)(p.ropes + spos * 32 + (cih >> 1));
;                   f32x4 r;
;                   r[0] = v[0] * cs.x - v[1] * sn.x;
;                   r[1] = v[0] * sn.x + v[1] * cs.x;
;                   r[2] = v[2] * cs.y - v[3] * sn.y;
;                   r[3] = v[2] * sn.y + v[3] * cs.y;
;                   v = r;
;                 }
;                 if (pn == 9) v = v * 0.125f;
;               }
;               o[2 * n] = pk_bf16(v[0], v[1]);
;               o[2 * n + 1] = pk_bf16(v[2], v[3]);
;             }
;             *(u32x4*)(Z + (size_t)row * ZW + bcol + bj * 128 + wc * 32 + fq * 8) = o;
.LBB0_302:
	v_cvt_pk_bf16_f32 v86, v86, v87
	v_cvt_pk_bf16_f32 v87, v88, v89
	v_cvt_pk_bf16_f32 v88, v82, v83
	v_cvt_pk_bf16_f32 v89, v84, v85
	ds_bpermute_b32 v86, v196, v86
	ds_bpermute_b32 v87, v196, v87
	ds_bpermute_b32 v88, v196, v88
	ds_bpermute_b32 v89, v196, v89
	s_waitcnt lgkmcnt(0)
	global_store_dwordx4 v[90:91], v[86:89], off offset:256
	v_mov_b64_e32 v[92:93], v[168:169]
	v_mov_b64_e32 v[94:95], v[170:171]
	v_or_b32_e32 v0, 48, v154
	v_lshlrev_b32_e32 v82, 3, v0
	v_or_b32_e32 v89, s13, v82
	v_bitop3_b32 v82, v82, 1, s13 bitop3:0x36
	v_lshl_add_u32 v88, v89, 2, s24
	v_lshl_add_u32 v82, v82, 2, s24
	ds_read_b32 v83, v88
	ds_read_b32 v82, v82
	v_add_u32_e32 v90, s22, v0
	v_lshlrev_b32_e32 v0, 7, v90
	v_readlane_b32 s60, v254, 45
	v_and_b32_e32 v0, 0x3ff80, v0
	s_waitcnt lgkmcnt(0)
	v_add_f32_e32 v82, v83, v82
	v_fmamk_f32 v82, v82, 0x3c800000, v236
	v_rsq_f32_e32 v86, v82
	v_readlane_b32 s66, v254, 51
	v_readlane_b32 s67, v254, 52
	v_readlane_b32 s68, v254, 53
	v_readlane_b32 s69, v254, 54
	v_pk_mul_f32 v[78:79], v[78:79], v[86:87] op_sel_hi:[1,0]
	v_pk_mul_f32 v[80:81], v[80:81], v[86:87] op_sel_hi:[1,0]
	s_and_b64 vcc, exec, s[40:41]
	v_lshl_add_u64 v[84:85], s[66:67], 0, v[0:1]
	v_lshl_add_u64 v[82:83], s[68:69], 0, v[0:1]
	v_lshl_add_u64 v[184:185], v[84:85], 0, v[182:183]
	global_load_dwordx4 v[186:189], v[184:185], off
	v_lshl_add_u64 v[184:185], v[82:83], 0, v[182:183]
	global_load_dwordx4 v[190:193], v[184:185], off
	v_readlane_b32 s61, v254, 46
	v_readlane_b32 s62, v254, 47
	v_readlane_b32 s63, v254, 48
	v_readlane_b32 s64, v254, 49
	v_readlane_b32 s65, v254, 50
	v_readlane_b32 s70, v254, 55
	v_readlane_b32 s71, v254, 56
	v_readlane_b32 s72, v254, 57
	v_readlane_b32 s73, v254, 58
	v_readlane_b32 s74, v254, 59
	v_readlane_b32 s75, v254, 60
	v_pk_mul_f32 v[80:81], v[94:95], v[80:81]
	v_pk_mul_f32 v[78:79], v[92:93], v[78:79]
	s_cbranch_vccnz .LBB0_304
	v_lshlrev_b32_e32 v0, 1, v140
	v_lshl_add_u64 v[92:93], v[84:85], 0, v[0:1]
	v_lshl_add_u64 v[94:95], v[82:83], 0, v[0:1]
	s_waitcnt vmcnt(0)
	v_mov_b64_e32 v[92:93], v[186:187]
	v_pk_mul_f32 v[98:99], v[78:79], v[92:93]
	v_mov_b64_e32 v[94:95], v[190:191]
	v_pk_mul_f32 v[96:97], v[78:79], v[94:95] op_sel:[1,0] op_sel_hi:[0,0]
	v_mov_b32_e32 v94, v93
	v_mul_f32_e32 v0, v81, v95
	v_pk_fma_f32 v[78:79], v[78:79], v[92:93], v[96:97] op_sel_hi:[1,0,1]
	v_pk_fma_f32 v[100:101], v[80:81], v[94:95], v[0:1] op_sel_hi:[1,1,0] neg_lo:[0,0,1] neg_hi:[0,0,1]
	v_mov_b32_e32 v92, v95
	v_mul_f32_e32 v0, v81, v93
	v_pk_fma_f32 v[92:93], v[80:81], v[92:93], v[0:1] op_sel_hi:[1,1,0]
	v_sub_f32_e32 v78, v98, v96
	v_mov_b32_e32 v80, v100
	v_mov_b32_e32 v81, v92

; template <int EPI>
; DI void gemm_epilogue(const Params& p, int layer, f32x4 (&acc)[2][2][4][2], int brow, int bcol, int pn, int wr, int wc,
;                       int fr, int fq, char* smem, int ksplit = -1) {
;     ...
;                 if (pn == 9) v = v * 0.125f;
;               }
;               o[2 * n] = pk_bf16(v[0], v[1]);
;               o[2 * n + 1] = pk_bf16(v[2], v[3]);
;             }
;             *(u32x4*)(Z + (size_t)row * ZW + bcol + bj * 128 + wc * 32 + fq * 8) = o;
.LBB0_306:
	v_pk_mul_f32 v[74:75], v[78:79], s[54:55] op_sel_hi:[1,0]
	v_pk_mul_f32 v[92:93], v[80:81], s[54:55] op_sel_hi:[1,0]
	v_cndmask_b32_e64 v75, v79, v75, s[0:1]
	v_cndmask_b32_e64 v0, v81, v93, s[0:1]
	v_cndmask_b32_e64 v80, v80, v92, s[0:1]
	v_cndmask_b32_e64 v74, v78, v74, s[0:1]
	v_cvt_pk_bf16_f32 v78, v74, v75
	v_cvt_pk_bf16_f32 v79, v80, v0
	v_mad_i64_i32 v[74:75], s[2:3], v90, s79, v[122:123]
	v_pk_mul_f32 v[80:81], v[76:77], s[54:55] op_sel_hi:[1,0]
	v_pk_mul_f32 v[90:91], v[86:87], s[54:55] op_sel_hi:[1,0]
	v_cndmask_b32_e64 v77, v77, v81, s[0:1]
	v_cndmask_b32_e64 v0, v87, v91, s[0:1]
	v_cndmask_b32_e64 v86, v86, v90, s[0:1]
	v_cndmask_b32_e64 v76, v76, v80, s[0:1]
	v_cvt_pk_bf16_f32 v80, v76, v77
	v_cvt_pk_bf16_f32 v81, v86, v0
	s_and_b64 vcc, exec, s[42:43]
	v_mov_b32_e32 v76, 1.0
	v_lshl_add_u64 v[74:75], v[74:75], 0, v[194:195]
	ds_bpermute_b32 v78, v196, v78
	ds_bpermute_b32 v79, v196, v79
	ds_bpermute_b32 v80, v196, v80
	ds_bpermute_b32 v81, v196, v81
	s_waitcnt lgkmcnt(0)
	global_store_dwordx4 v[74:75], v[78:81], off
	s_cbranch_vccnz .LBB0_309
	v_xor_b32_e32 v0, 5, v89
	v_lshl_add_u32 v0, v0, 2, 0
	v_add_u32_e32 v0, 0x20000, v0
	ds_read_b32 v76, v88 offset:16
	ds_read_b32 v0, v0
	s_waitcnt lgkmcnt(0)
	v_add_f32_e32 v0, v76, v0
	v_fmamk_f32 v0, v0, 0x3c800000, v236
	v_rsq_f32_e32 v76, v0
	s_and_b64 vcc, exec, s[42:43]
	v_mov_b32_e32 v77, v76
	s_cbranch_vccz .LBB0_310

; template <int EPI>
; DI void gemm_epilogue(const Params& p, int layer, f32x4 (&acc)[2][2][4][2], int brow, int bcol, int pn, int wr, int wc,
;                       int fr, int fq, char* smem, int ksplit = -1) {
;     ...
;           const int rl = ai * 128 + wr * 64 + m * 16 + fr;
;           const int row = brow + rl;
;           const int spos = row & (SEQ - 1);
; #pragma unroll
;           for (int bj = 0; bj < 2; ++bj) {
;             const bool normed = (pn == 9) || (bj == 0);
;             float rs = 1.f;
;             if (normed) {
;               float tot = xch[rl * 8 + bj * 4 + wc] + xch[rl * 8 + bj * 4 + (wc ^ 1)];
;               rs = __builtin_amdgcn_rsqf(tot * (1.f / 64.f) + EPSN);
;             }
;             u32x4 o;
; #pragma unroll
;             for (int n = 0; n < 2; ++n) {
;               const int cih = (wc & 1) * 32 + fq * 8 + n * 4;
;               f32x4 v = acc[ai][bj][m][n];
;               if (normed) {
;                 f32x4 g = *(const f32x4*)(gq + cih);
;                 v = v * rs * g;
;                 if (latent) {
;                   const float2 cs = *(const float2*)(p.ropec + spos * 32 + (cih >> 1));
;                   const float2 sn = *(const float2*)(p.ropes + spos * 32 + (cih >> 1));
;                   f32x4 r;
;                   r[0] = v[0] * cs.x - v[1] * sn.x;
;                   r[1] = v[0] * sn.x + v[1] * cs.x;
;                   r[2] = v[2] * cs.y - v[3] * sn.y;
;                   r[3] = v[2] * sn.y + v[3] * cs.y;
;                   v = r;
;                 }
;                 if (pn == 9) v = v * 0.125f;
;               }
;               o[2 * n] = pk_bf16(v[0], v[1]);
;               o[2 * n + 1] = pk_bf16(v[2], v[3]);
;             }
;             *(u32x4*)(Z + (size_t)row * ZW + bcol + bj * 128 + wc * 32 + fq * 8) = o;
.LBB0_316:
	v_cvt_pk_bf16_f32 v70, v70, v71
	v_cvt_pk_bf16_f32 v71, v72, v73
	v_cvt_pk_bf16_f32 v72, v66, v67
	v_cvt_pk_bf16_f32 v73, v68, v69
	ds_bpermute_b32 v70, v196, v70
	ds_bpermute_b32 v71, v196, v71
	ds_bpermute_b32 v72, v196, v72
	ds_bpermute_b32 v73, v196, v73
	s_waitcnt lgkmcnt(0)
	global_store_dwordx4 v[74:75], v[70:73], off offset:256
	v_add_u32_e32 v0, 0x80, v154
	v_mov_b64_e32 v[76:77], v[168:169]
	v_mov_b64_e32 v[78:79], v[170:171]
	v_lshlrev_b32_e32 v66, 3, v0
	v_or_b32_e32 v73, s13, v66
	v_bitop3_b32 v66, v66, 1, s13 bitop3:0x36
	v_lshl_add_u32 v72, v73, 2, s24
	v_lshl_add_u32 v66, v66, 2, s24
	ds_read_b32 v67, v72
	ds_read_b32 v66, v66
	v_add_u32_e32 v74, s22, v0
	v_lshlrev_b32_e32 v0, 7, v74
	v_readlane_b32 s60, v254, 45
	v_and_b32_e32 v0, 0x3e780, v0
	s_waitcnt lgkmcnt(0)
	v_add_f32_e32 v66, v67, v66
	v_fmamk_f32 v66, v66, 0x3c800000, v236
	v_rsq_f32_e32 v70, v66
	v_readlane_b32 s66, v254, 51
	v_readlane_b32 s67, v254, 52
	v_readlane_b32 s68, v254, 53
	v_readlane_b32 s69, v254, 54
	v_pk_mul_f32 v[62:63], v[62:63], v[70:71] op_sel_hi:[1,0]
	v_pk_mul_f32 v[64:65], v[64:65], v[70:71] op_sel_hi:[1,0]
	s_and_b64 vcc, exec, s[40:41]
	v_lshl_add_u64 v[68:69], s[66:67], 0, v[0:1]
	v_lshl_add_u64 v[66:67], s[68:69], 0, v[0:1]
	v_lshl_add_u64 v[184:185], v[68:69], 0, v[182:183]
	global_load_dwordx4 v[186:189], v[184:185], off
	v_lshl_add_u64 v[184:185], v[66:67], 0, v[182:183]
	global_load_dwordx4 v[190:193], v[184:185], off
	v_readlane_b32 s61, v254, 46
	v_readlane_b32 s62, v254, 47
	v_readlane_b32 s63, v254, 48
	v_readlane_b32 s64, v254, 49
	v_readlane_b32 s65, v254, 50
	v_readlane_b32 s70, v254, 55
	v_readlane_b32 s71, v254, 56
	v_readlane_b32 s72, v254, 57
	v_readlane_b32 s73, v254, 58
	v_readlane_b32 s74, v254, 59
	v_readlane_b32 s75, v254, 60
	v_pk_mul_f32 v[64:65], v[78:79], v[64:65]
	v_pk_mul_f32 v[62:63], v[76:77], v[62:63]
	s_cbranch_vccnz .LBB0_318
	v_lshlrev_b32_e32 v0, 1, v140
	v_lshl_add_u64 v[76:77], v[68:69], 0, v[0:1]
	v_lshl_add_u64 v[78:79], v[66:67], 0, v[0:1]
	s_waitcnt vmcnt(0)
	v_mov_b64_e32 v[76:77], v[186:187]
	v_pk_mul_f32 v[82:83], v[62:63], v[76:77]
	v_mov_b64_e32 v[78:79], v[190:191]
	v_pk_mul_f32 v[80:81], v[62:63], v[78:79] op_sel:[1,0] op_sel_hi:[0,0]
	v_mov_b32_e32 v78, v77
	v_mul_f32_e32 v0, v65, v79
	v_pk_fma_f32 v[62:63], v[62:63], v[76:77], v[80:81] op_sel_hi:[1,0,1]
	v_pk_fma_f32 v[84:85], v[64:65], v[78:79], v[0:1] op_sel_hi:[1,1,0] neg_lo:[0,0,1] neg_hi:[0,0,1]
	v_mov_b32_e32 v76, v79
	v_mul_f32_e32 v0, v65, v77
	v_pk_fma_f32 v[76:77], v[64:65], v[76:77], v[0:1] op_sel_hi:[1,1,0]
	v_sub_f32_e32 v62, v82, v80
	v_mov_b32_e32 v64, v84
	v_mov_b32_e32 v65, v76

; template <int EPI>
; DI void gemm_epilogue(const Params& p, int layer, f32x4 (&acc)[2][2][4][2], int brow, int bcol, int pn, int wr, int wc,
;                       int fr, int fq, char* smem, int ksplit = -1) {
;     ...
;             if (normed) {
;               float tot = xch[rl * 8 + bj * 4 + wc] + xch[rl * 8 + bj * 4 + (wc ^ 1)];
;               rs = __builtin_amdgcn_rsqf(tot * (1.f / 64.f) + EPSN);
;             }
;             u32x4 o;
; #pragma unroll
;             for (int n = 0; n < 2; ++n) {
;               const int cih = (wc & 1) * 32 + fq * 8 + n * 4;
;               f32x4 v = acc[ai][bj][m][n];
;               if (normed) {
;                 f32x4 g = *(const f32x4*)(gq + cih);
;                 v = v * rs * g;
;                 if (latent) {
;                   const float2 cs = *(const float2*)(p.ropec + spos * 32 + (cih >> 1));
;                   const float2 sn = *(const float2*)(p.ropes + spos * 32 + (cih >> 1));
;                   f32x4 r;
;                   r[0] = v[0] * cs.x - v[1] * sn.x;
;                   r[1] = v[0] * sn.x + v[1] * cs.x;
;                   r[2] = v[2] * cs.y - v[3] * sn.y;
;                   r[3] = v[2] * sn.y + v[3] * cs.y;
;                   v = r;
;                 }
;                 if (pn == 9) v = v * 0.125f;
;               }
;               o[2 * n] = pk_bf16(v[0], v[1]);
;               o[2 * n + 1] = pk_bf16(v[2], v[3]);
;             }
;             *(u32x4*)(Z + (size_t)row * ZW + bcol + bj * 128 + wc * 32 + fq * 8) = o;
.LBB0_320:
	v_pk_mul_f32 v[58:59], v[62:63], s[54:55] op_sel_hi:[1,0]
	v_pk_mul_f32 v[76:77], v[64:65], s[54:55] op_sel_hi:[1,0]
	v_cndmask_b32_e64 v59, v63, v59, s[0:1]
	v_cndmask_b32_e64 v0, v65, v77, s[0:1]
	v_cndmask_b32_e64 v64, v64, v76, s[0:1]
	v_cndmask_b32_e64 v58, v62, v58, s[0:1]
	v_cvt_pk_bf16_f32 v62, v58, v59
	v_cvt_pk_bf16_f32 v63, v64, v0
	v_mad_i64_i32 v[58:59], s[2:3], v74, s79, v[122:123]
	v_pk_mul_f32 v[64:65], v[60:61], s[54:55] op_sel_hi:[1,0]
	v_pk_mul_f32 v[74:75], v[70:71], s[54:55] op_sel_hi:[1,0]
	v_cndmask_b32_e64 v61, v61, v65, s[0:1]
	v_cndmask_b32_e64 v0, v71, v75, s[0:1]
	v_cndmask_b32_e64 v70, v70, v74, s[0:1]
	v_cndmask_b32_e64 v60, v60, v64, s[0:1]
	v_cvt_pk_bf16_f32 v64, v60, v61
	v_cvt_pk_bf16_f32 v65, v70, v0
	s_and_b64 vcc, exec, s[42:43]
	v_mov_b32_e32 v60, 1.0
	v_lshl_add_u64 v[58:59], v[58:59], 0, v[194:195]
	ds_bpermute_b32 v62, v196, v62
	ds_bpermute_b32 v63, v196, v63
	ds_bpermute_b32 v64, v196, v64
	ds_bpermute_b32 v65, v196, v65
	s_waitcnt lgkmcnt(0)
	global_store_dwordx4 v[58:59], v[62:65], off
	s_cbranch_vccnz .LBB0_323
	v_xor_b32_e32 v0, 5, v73
	v_lshl_add_u32 v0, v0, 2, 0
	v_add_u32_e32 v0, 0x20000, v0
	ds_read_b32 v60, v72 offset:16
	ds_read_b32 v0, v0
	s_waitcnt lgkmcnt(0)
	v_add_f32_e32 v0, v60, v0
	v_fmamk_f32 v0, v0, 0x3c800000, v236
	v_rsq_f32_e32 v60, v0
	s_and_b64 vcc, exec, s[42:43]
	v_mov_b32_e32 v61, v60
	s_cbranch_vccz .LBB0_324

; template <int EPI>
; DI void gemm_epilogue(const Params& p, int layer, f32x4 (&acc)[2][2][4][2], int brow, int bcol, int pn, int wr, int wc,
;                       int fr, int fq, char* smem, int ksplit = -1) {
;     ...
;           const int rl = ai * 128 + wr * 64 + m * 16 + fr;
;           const int row = brow + rl;
;           const int spos = row & (SEQ - 1);
; #pragma unroll
;           for (int bj = 0; bj < 2; ++bj) {
;             const bool normed = (pn == 9) || (bj == 0);
;             float rs = 1.f;
;             if (normed) {
;               float tot = xch[rl * 8 + bj * 4 + wc] + xch[rl * 8 + bj * 4 + (wc ^ 1)];
;               rs = __builtin_amdgcn_rsqf(tot * (1.f / 64.f) + EPSN);
;             }
;             u32x4 o;
; #pragma unroll
;             for (int n = 0; n < 2; ++n) {
;               const int cih = (wc & 1) * 32 + fq * 8 + n * 4;
;               f32x4 v = acc[ai][bj][m][n];
;               if (normed) {
;                 f32x4 g = *(const f32x4*)(gq + cih);
;                 v = v * rs * g;
;                 if (latent) {
;                   const float2 cs = *(const float2*)(p.ropec + spos * 32 + (cih >> 1));
;                   const float2 sn = *(const float2*)(p.ropes + spos * 32 + (cih >> 1));
;                   f32x4 r;
;                   r[0] = v[0] * cs.x - v[1] * sn.x;
;                   r[1] = v[0] * sn.x + v[1] * cs.x;
;                   r[2] = v[2] * cs.y - v[3] * sn.y;
;                   r[3] = v[2] * sn.y + v[3] * cs.y;
;                   v = r;
;                 }
;                 if (pn == 9) v = v * 0.125f;
;               }
;               o[2 * n] = pk_bf16(v[0], v[1]);
;               o[2 * n + 1] = pk_bf16(v[2], v[3]);
;             }
;             *(u32x4*)(Z + (size_t)row * ZW + bcol + bj * 128 + wc * 32 + fq * 8) = o;
.LBB0_330:
	v_cvt_pk_bf16_f32 v54, v54, v55
	v_cvt_pk_bf16_f32 v55, v56, v57
	v_cvt_pk_bf16_f32 v56, v50, v51
	v_cvt_pk_bf16_f32 v57, v52, v53
	ds_bpermute_b32 v54, v196, v54
	ds_bpermute_b32 v55, v196, v55
	ds_bpermute_b32 v56, v196, v56
	ds_bpermute_b32 v57, v196, v57
	s_waitcnt lgkmcnt(0)
	global_store_dwordx4 v[58:59], v[54:57], off offset:256
	v_mov_b64_e32 v[60:61], v[168:169]
	v_mov_b64_e32 v[62:63], v[170:171]
	v_add_u32_e32 v0, 0x90, v154
	v_lshlrev_b32_e32 v50, 3, v0
	v_or_b32_e32 v57, s13, v50
	v_bitop3_b32 v50, v50, 1, s13 bitop3:0x36
	v_lshl_add_u32 v56, v57, 2, s24
	v_lshl_add_u32 v50, v50, 2, s24
	ds_read_b32 v51, v56
	ds_read_b32 v50, v50
	v_add_u32_e32 v58, s22, v0
	v_lshlrev_b32_e32 v0, 7, v58
	v_readlane_b32 s60, v254, 45
	v_and_b32_e32 v0, 0x3ef80, v0
	s_waitcnt lgkmcnt(0)
	v_add_f32_e32 v50, v51, v50
	v_fmamk_f32 v50, v50, 0x3c800000, v236
	v_rsq_f32_e32 v54, v50
	v_readlane_b32 s66, v254, 51
	v_readlane_b32 s67, v254, 52
	v_readlane_b32 s68, v254, 53
	v_readlane_b32 s69, v254, 54
	v_pk_mul_f32 v[46:47], v[46:47], v[54:55] op_sel_hi:[1,0]
	v_pk_mul_f32 v[48:49], v[48:49], v[54:55] op_sel_hi:[1,0]
	s_and_b64 vcc, exec, s[40:41]
	v_lshl_add_u64 v[52:53], s[66:67], 0, v[0:1]
	v_lshl_add_u64 v[50:51], s[68:69], 0, v[0:1]
	v_lshl_add_u64 v[184:185], v[52:53], 0, v[182:183]
	global_load_dwordx4 v[186:189], v[184:185], off
	v_lshl_add_u64 v[184:185], v[50:51], 0, v[182:183]
	global_load_dwordx4 v[190:193], v[184:185], off
	v_readlane_b32 s61, v254, 46
	v_readlane_b32 s62, v254, 47
	v_readlane_b32 s63, v254, 48
	v_readlane_b32 s64, v254, 49
	v_readlane_b32 s65, v254, 50
	v_readlane_b32 s70, v254, 55
	v_readlane_b32 s71, v254, 56
	v_readlane_b32 s72, v254, 57
	v_readlane_b32 s73, v254, 58
	v_readlane_b32 s74, v254, 59
	v_readlane_b32 s75, v254, 60
	v_pk_mul_f32 v[48:49], v[62:63], v[48:49]
	v_pk_mul_f32 v[46:47], v[60:61], v[46:47]
	s_cbranch_vccnz .LBB0_332
	v_lshlrev_b32_e32 v0, 1, v140
	v_lshl_add_u64 v[60:61], v[52:53], 0, v[0:1]
	v_lshl_add_u64 v[62:63], v[50:51], 0, v[0:1]
	s_waitcnt vmcnt(0)
	v_mov_b64_e32 v[60:61], v[186:187]
	v_pk_mul_f32 v[66:67], v[46:47], v[60:61]
	v_mov_b64_e32 v[62:63], v[190:191]
	v_pk_mul_f32 v[64:65], v[46:47], v[62:63] op_sel:[1,0] op_sel_hi:[0,0]
	v_mov_b32_e32 v62, v61
	v_mul_f32_e32 v0, v49, v63
	v_pk_fma_f32 v[46:47], v[46:47], v[60:61], v[64:65] op_sel_hi:[1,0,1]
	v_pk_fma_f32 v[68:69], v[48:49], v[62:63], v[0:1] op_sel_hi:[1,1,0] neg_lo:[0,0,1] neg_hi:[0,0,1]
	v_mov_b32_e32 v60, v63
	v_mul_f32_e32 v0, v49, v61
	v_pk_fma_f32 v[60:61], v[48:49], v[60:61], v[0:1] op_sel_hi:[1,1,0]
	v_sub_f32_e32 v46, v66, v64
	v_mov_b32_e32 v48, v68
	v_mov_b32_e32 v49, v60

; template <int EPI>
; DI void gemm_epilogue(const Params& p, int layer, f32x4 (&acc)[2][2][4][2], int brow, int bcol, int pn, int wr, int wc,
;                       int fr, int fq, char* smem, int ksplit = -1) {
;     ...
;             if (normed) {
;               float tot = xch[rl * 8 + bj * 4 + wc] + xch[rl * 8 + bj * 4 + (wc ^ 1)];
;               rs = __builtin_amdgcn_rsqf(tot * (1.f / 64.f) + EPSN);
;             }
;             u32x4 o;
; #pragma unroll
;             for (int n = 0; n < 2; ++n) {
;               const int cih = (wc & 1) * 32 + fq * 8 + n * 4;
;               f32x4 v = acc[ai][bj][m][n];
;               if (normed) {
;                 f32x4 g = *(const f32x4*)(gq + cih);
;                 v = v * rs * g;
;                 if (latent) {
;                   const float2 cs = *(const float2*)(p.ropec + spos * 32 + (cih >> 1));
;                   const float2 sn = *(const float2*)(p.ropes + spos * 32 + (cih >> 1));
;                   f32x4 r;
;                   r[0] = v[0] * cs.x - v[1] * sn.x;
;                   r[1] = v[0] * sn.x + v[1] * cs.x;
;                   r[2] = v[2] * cs.y - v[3] * sn.y;
;                   r[3] = v[2] * sn.y + v[3] * cs.y;
;                   v = r;
;                 }
;                 if (pn == 9) v = v * 0.125f;
;               }
;               o[2 * n] = pk_bf16(v[0], v[1]);
;               o[2 * n + 1] = pk_bf16(v[2], v[3]);
;             }
;             *(u32x4*)(Z + (size_t)row * ZW + bcol + bj * 128 + wc * 32 + fq * 8) = o;
.LBB0_334:
	v_pk_mul_f32 v[42:43], v[46:47], s[54:55] op_sel_hi:[1,0]
	v_pk_mul_f32 v[60:61], v[48:49], s[54:55] op_sel_hi:[1,0]
	v_cndmask_b32_e64 v43, v47, v43, s[0:1]
	v_cndmask_b32_e64 v0, v49, v61, s[0:1]
	v_cndmask_b32_e64 v48, v48, v60, s[0:1]
	v_cndmask_b32_e64 v42, v46, v42, s[0:1]
	v_cvt_pk_bf16_f32 v46, v42, v43
	v_cvt_pk_bf16_f32 v47, v48, v0
	v_mad_i64_i32 v[42:43], s[2:3], v58, s79, v[122:123]
	v_pk_mul_f32 v[48:49], v[44:45], s[54:55] op_sel_hi:[1,0]
	v_pk_mul_f32 v[58:59], v[54:55], s[54:55] op_sel_hi:[1,0]
	v_cndmask_b32_e64 v45, v45, v49, s[0:1]
	v_cndmask_b32_e64 v0, v55, v59, s[0:1]
	v_cndmask_b32_e64 v54, v54, v58, s[0:1]
	v_cndmask_b32_e64 v44, v44, v48, s[0:1]
	v_cvt_pk_bf16_f32 v48, v44, v45
	v_cvt_pk_bf16_f32 v49, v54, v0
	s_and_b64 vcc, exec, s[42:43]
	v_mov_b32_e32 v44, 1.0
	v_lshl_add_u64 v[42:43], v[42:43], 0, v[194:195]
	ds_bpermute_b32 v46, v196, v46
	ds_bpermute_b32 v47, v196, v47
	ds_bpermute_b32 v48, v196, v48
	ds_bpermute_b32 v49, v196, v49
	s_waitcnt lgkmcnt(0)
	global_store_dwordx4 v[42:43], v[46:49], off
	s_cbranch_vccnz .LBB0_337
	v_xor_b32_e32 v0, 5, v57
	v_lshl_add_u32 v0, v0, 2, 0
	v_add_u32_e32 v0, 0x20000, v0
	ds_read_b32 v44, v56 offset:16
	ds_read_b32 v0, v0
	s_waitcnt lgkmcnt(0)
	v_add_f32_e32 v0, v44, v0
	v_fmamk_f32 v0, v0, 0x3c800000, v236
	v_rsq_f32_e32 v44, v0
	s_and_b64 vcc, exec, s[42:43]
	v_mov_b32_e32 v45, v44
	s_cbranch_vccz .LBB0_338

; template <int EPI>
; DI void gemm_epilogue(const Params& p, int layer, f32x4 (&acc)[2][2][4][2], int brow, int bcol, int pn, int wr, int wc,
;                       int fr, int fq, char* smem, int ksplit = -1) {
;     ...
;           const int rl = ai * 128 + wr * 64 + m * 16 + fr;
;           const int row = brow + rl;
;           const int spos = row & (SEQ - 1);
; #pragma unroll
;           for (int bj = 0; bj < 2; ++bj) {
;             const bool normed = (pn == 9) || (bj == 0);
;             float rs = 1.f;
;             if (normed) {
;               float tot = xch[rl * 8 + bj * 4 + wc] + xch[rl * 8 + bj * 4 + (wc ^ 1)];
;               rs = __builtin_amdgcn_rsqf(tot * (1.f / 64.f) + EPSN);
;             }
;             u32x4 o;
; #pragma unroll
;             for (int n = 0; n < 2; ++n) {
;               const int cih = (wc & 1) * 32 + fq * 8 + n * 4;
;               f32x4 v = acc[ai][bj][m][n];
;               if (normed) {
;                 f32x4 g = *(const f32x4*)(gq + cih);
;                 v = v * rs * g;
;                 if (latent) {
;                   const float2 cs = *(const float2*)(p.ropec + spos * 32 + (cih >> 1));
;                   const float2 sn = *(const float2*)(p.ropes + spos * 32 + (cih >> 1));
;                   f32x4 r;
;                   r[0] = v[0] * cs.x - v[1] * sn.x;
;                   r[1] = v[0] * sn.x + v[1] * cs.x;
;                   r[2] = v[2] * cs.y - v[3] * sn.y;
;                   r[3] = v[2] * sn.y + v[3] * cs.y;
;                   v = r;
;                 }
;                 if (pn == 9) v = v * 0.125f;
;               }
;               o[2 * n] = pk_bf16(v[0], v[1]);
;               o[2 * n + 1] = pk_bf16(v[2], v[3]);
;             }
;             *(u32x4*)(Z + (size_t)row * ZW + bcol + bj * 128 + wc * 32 + fq * 8) = o;
.LBB0_344:
	v_cvt_pk_bf16_f32 v38, v38, v39
	v_cvt_pk_bf16_f32 v39, v40, v41
	v_cvt_pk_bf16_f32 v40, v34, v35
	v_cvt_pk_bf16_f32 v41, v36, v37
	ds_bpermute_b32 v38, v196, v38
	ds_bpermute_b32 v39, v196, v39
	ds_bpermute_b32 v40, v196, v40
	ds_bpermute_b32 v41, v196, v41
	s_waitcnt lgkmcnt(0)
	global_store_dwordx4 v[42:43], v[38:41], off offset:256
	v_mov_b64_e32 v[44:45], v[168:169]
	v_mov_b64_e32 v[46:47], v[170:171]
	v_add_u32_e32 v0, 0xa0, v154
	v_lshlrev_b32_e32 v34, 3, v0
	v_or_b32_e32 v41, s13, v34
	v_bitop3_b32 v34, v34, 1, s13 bitop3:0x36
	v_lshl_add_u32 v40, v41, 2, s24
	v_lshl_add_u32 v34, v34, 2, s24
	ds_read_b32 v35, v40
	ds_read_b32 v34, v34
	v_add_u32_e32 v42, s22, v0
	v_lshlrev_b32_e32 v0, 7, v42
	v_readlane_b32 s60, v254, 45
	v_and_b32_e32 v0, 0x3f780, v0
	s_waitcnt lgkmcnt(0)
	v_add_f32_e32 v34, v35, v34
	v_fmamk_f32 v34, v34, 0x3c800000, v236
	v_rsq_f32_e32 v38, v34
	v_readlane_b32 s66, v254, 51
	v_readlane_b32 s67, v254, 52
	v_readlane_b32 s68, v254, 53
	v_readlane_b32 s69, v254, 54
	v_pk_mul_f32 v[30:31], v[30:31], v[38:39] op_sel_hi:[1,0]
	v_pk_mul_f32 v[32:33], v[32:33], v[38:39] op_sel_hi:[1,0]
	s_and_b64 vcc, exec, s[40:41]
	v_lshl_add_u64 v[36:37], s[66:67], 0, v[0:1]
	v_lshl_add_u64 v[34:35], s[68:69], 0, v[0:1]
	v_lshl_add_u64 v[184:185], v[36:37], 0, v[182:183]
	global_load_dwordx4 v[186:189], v[184:185], off
	v_lshl_add_u64 v[184:185], v[34:35], 0, v[182:183]
	global_load_dwordx4 v[190:193], v[184:185], off
	v_readlane_b32 s61, v254, 46
	v_readlane_b32 s62, v254, 47
	v_readlane_b32 s63, v254, 48
	v_readlane_b32 s64, v254, 49
	v_readlane_b32 s65, v254, 50
	v_readlane_b32 s70, v254, 55
	v_readlane_b32 s71, v254, 56
	v_readlane_b32 s72, v254, 57
	v_readlane_b32 s73, v254, 58
	v_readlane_b32 s74, v254, 59
	v_readlane_b32 s75, v254, 60
	v_pk_mul_f32 v[32:33], v[46:47], v[32:33]
	v_pk_mul_f32 v[30:31], v[44:45], v[30:31]
	s_cbranch_vccnz .LBB0_346
	v_lshlrev_b32_e32 v0, 1, v140
	v_lshl_add_u64 v[44:45], v[36:37], 0, v[0:1]
	v_lshl_add_u64 v[46:47], v[34:35], 0, v[0:1]
	s_waitcnt vmcnt(0)
	v_mov_b64_e32 v[44:45], v[186:187]
	v_pk_mul_f32 v[50:51], v[30:31], v[44:45]
	v_mov_b64_e32 v[46:47], v[190:191]
	v_pk_mul_f32 v[48:49], v[30:31], v[46:47] op_sel:[1,0] op_sel_hi:[0,0]
	v_mov_b32_e32 v46, v45
	v_mul_f32_e32 v0, v33, v47
	v_pk_fma_f32 v[30:31], v[30:31], v[44:45], v[48:49] op_sel_hi:[1,0,1]
	v_pk_fma_f32 v[52:53], v[32:33], v[46:47], v[0:1] op_sel_hi:[1,1,0] neg_lo:[0,0,1] neg_hi:[0,0,1]
	v_mov_b32_e32 v44, v47
	v_mul_f32_e32 v0, v33, v45
	v_pk_fma_f32 v[44:45], v[32:33], v[44:45], v[0:1] op_sel_hi:[1,1,0]
	v_sub_f32_e32 v30, v50, v48
	v_mov_b32_e32 v32, v52
	v_mov_b32_e32 v33, v44

; template <int EPI>
; DI void gemm_epilogue(const Params& p, int layer, f32x4 (&acc)[2][2][4][2], int brow, int bcol, int pn, int wr, int wc,
;                       int fr, int fq, char* smem, int ksplit = -1) {
;     ...
;             if (normed) {
;               float tot = xch[rl * 8 + bj * 4 + wc] + xch[rl * 8 + bj * 4 + (wc ^ 1)];
;               rs = __builtin_amdgcn_rsqf(tot * (1.f / 64.f) + EPSN);
;             }
;             u32x4 o;
; #pragma unroll
;             for (int n = 0; n < 2; ++n) {
;               const int cih = (wc & 1) * 32 + fq * 8 + n * 4;
;               f32x4 v = acc[ai][bj][m][n];
;               if (normed) {
;                 f32x4 g = *(const f32x4*)(gq + cih);
;                 v = v * rs * g;
;                 if (latent) {
;                   const float2 cs = *(const float2*)(p.ropec + spos * 32 + (cih >> 1));
;                   const float2 sn = *(const float2*)(p.ropes + spos * 32 + (cih >> 1));
;                   f32x4 r;
;                   r[0] = v[0] * cs.x - v[1] * sn.x;
;                   r[1] = v[0] * sn.x + v[1] * cs.x;
;                   r[2] = v[2] * cs.y - v[3] * sn.y;
;                   r[3] = v[2] * sn.y + v[3] * cs.y;
;                   v = r;
;                 }
;                 if (pn == 9) v = v * 0.125f;
;               }
;               o[2 * n] = pk_bf16(v[0], v[1]);
;               o[2 * n + 1] = pk_bf16(v[2], v[3]);
;             }
;             *(u32x4*)(Z + (size_t)row * ZW + bcol + bj * 128 + wc * 32 + fq * 8) = o;
.LBB0_348:
	v_pk_mul_f32 v[26:27], v[30:31], s[54:55] op_sel_hi:[1,0]
	v_pk_mul_f32 v[44:45], v[32:33], s[54:55] op_sel_hi:[1,0]
	v_cndmask_b32_e64 v27, v31, v27, s[0:1]
	v_cndmask_b32_e64 v0, v33, v45, s[0:1]
	v_cndmask_b32_e64 v32, v32, v44, s[0:1]
	v_cndmask_b32_e64 v26, v30, v26, s[0:1]
	v_cvt_pk_bf16_f32 v30, v26, v27
	v_cvt_pk_bf16_f32 v31, v32, v0
	v_mad_i64_i32 v[26:27], s[2:3], v42, s79, v[122:123]
	v_pk_mul_f32 v[32:33], v[28:29], s[54:55] op_sel_hi:[1,0]
	v_pk_mul_f32 v[42:43], v[38:39], s[54:55] op_sel_hi:[1,0]
	v_cndmask_b32_e64 v29, v29, v33, s[0:1]
	v_cndmask_b32_e64 v0, v39, v43, s[0:1]
	v_cndmask_b32_e64 v38, v38, v42, s[0:1]
	v_cndmask_b32_e64 v28, v28, v32, s[0:1]
	v_cvt_pk_bf16_f32 v32, v28, v29
	v_cvt_pk_bf16_f32 v33, v38, v0
	s_and_b64 vcc, exec, s[42:43]
	v_mov_b32_e32 v28, 1.0
	v_lshl_add_u64 v[26:27], v[26:27], 0, v[194:195]
	ds_bpermute_b32 v30, v196, v30
	ds_bpermute_b32 v31, v196, v31
	ds_bpermute_b32 v32, v196, v32
	ds_bpermute_b32 v33, v196, v33
	s_waitcnt lgkmcnt(0)
	global_store_dwordx4 v[26:27], v[30:33], off
	s_cbranch_vccnz .LBB0_351
	v_xor_b32_e32 v0, 5, v41
	v_lshl_add_u32 v0, v0, 2, 0
	v_add_u32_e32 v0, 0x20000, v0
	ds_read_b32 v28, v40 offset:16
	ds_read_b32 v0, v0
	s_waitcnt lgkmcnt(0)
	v_add_f32_e32 v0, v28, v0
	v_fmamk_f32 v0, v0, 0x3c800000, v236
	v_rsq_f32_e32 v28, v0
	s_and_b64 vcc, exec, s[42:43]
	v_mov_b32_e32 v29, v28
	s_cbranch_vccz .LBB0_352

; template <int EPI>
; DI void gemm_epilogue(const Params& p, int layer, f32x4 (&acc)[2][2][4][2], int brow, int bcol, int pn, int wr, int wc,
;                       int fr, int fq, char* smem, int ksplit = -1) {
;     ...
;           const int rl = ai * 128 + wr * 64 + m * 16 + fr;
;           const int row = brow + rl;
;           const int spos = row & (SEQ - 1);
; #pragma unroll
;           for (int bj = 0; bj < 2; ++bj) {
;             const bool normed = (pn == 9) || (bj == 0);
;             float rs = 1.f;
;             if (normed) {
;               float tot = xch[rl * 8 + bj * 4 + wc] + xch[rl * 8 + bj * 4 + (wc ^ 1)];
;               rs = __builtin_amdgcn_rsqf(tot * (1.f / 64.f) + EPSN);
;             }
;             u32x4 o;
; #pragma unroll
;             for (int n = 0; n < 2; ++n) {
;               const int cih = (wc & 1) * 32 + fq * 8 + n * 4;
;               f32x4 v = acc[ai][bj][m][n];
;               if (normed) {
;                 f32x4 g = *(const f32x4*)(gq + cih);
;                 v = v * rs * g;
;                 if (latent) {
;                   const float2 cs = *(const float2*)(p.ropec + spos * 32 + (cih >> 1));
;                   const float2 sn = *(const float2*)(p.ropes + spos * 32 + (cih >> 1));
;                   f32x4 r;
;                   r[0] = v[0] * cs.x - v[1] * sn.x;
;                   r[1] = v[0] * sn.x + v[1] * cs.x;
;                   r[2] = v[2] * cs.y - v[3] * sn.y;
;                   r[3] = v[2] * sn.y + v[3] * cs.y;
;                   v = r;
;                 }
;                 if (pn == 9) v = v * 0.125f;
;               }
;               o[2 * n] = pk_bf16(v[0], v[1]);
;               o[2 * n + 1] = pk_bf16(v[2], v[3]);
;             }
;             *(u32x4*)(Z + (size_t)row * ZW + bcol + bj * 128 + wc * 32 + fq * 8) = o;
.LBB0_358:
	v_cvt_pk_bf16_f32 v22, v22, v23
	v_cvt_pk_bf16_f32 v23, v24, v25
	v_cvt_pk_bf16_f32 v24, v18, v19
	v_cvt_pk_bf16_f32 v25, v20, v21
	ds_bpermute_b32 v22, v196, v22
	ds_bpermute_b32 v23, v196, v23
	ds_bpermute_b32 v24, v196, v24
	ds_bpermute_b32 v25, v196, v25
	s_waitcnt lgkmcnt(0)
	global_store_dwordx4 v[26:27], v[22:25], off offset:256
	v_mov_b64_e32 v[28:29], v[168:169]
	v_mov_b64_e32 v[30:31], v[170:171]
	v_add_u32_e32 v0, 0xb0, v154
	v_lshlrev_b32_e32 v18, 3, v0
	v_or_b32_e32 v25, s13, v18
	v_bitop3_b32 v18, v18, 1, s13 bitop3:0x36
	v_lshl_add_u32 v24, v25, 2, s24
	v_lshl_add_u32 v18, v18, 2, s24
	ds_read_b32 v19, v24
	ds_read_b32 v18, v18
	v_add_u32_e32 v26, s22, v0
	v_lshlrev_b32_e32 v0, 7, v26
	v_readlane_b32 s60, v254, 45
	v_and_b32_e32 v0, 0x3ff80, v0
	s_waitcnt lgkmcnt(0)
	v_add_f32_e32 v18, v19, v18
	v_fmamk_f32 v18, v18, 0x3c800000, v236
	v_rsq_f32_e32 v22, v18
	v_readlane_b32 s66, v254, 51
	v_readlane_b32 s67, v254, 52
	v_readlane_b32 s68, v254, 53
	v_readlane_b32 s69, v254, 54
	v_pk_mul_f32 v[14:15], v[14:15], v[22:23] op_sel_hi:[1,0]
	v_pk_mul_f32 v[16:17], v[16:17], v[22:23] op_sel_hi:[1,0]
	s_and_b64 vcc, exec, s[40:41]
	v_lshl_add_u64 v[20:21], s[66:67], 0, v[0:1]
	v_lshl_add_u64 v[18:19], s[68:69], 0, v[0:1]
	v_lshl_add_u64 v[184:185], v[20:21], 0, v[182:183]
	global_load_dwordx4 v[186:189], v[184:185], off
	v_lshl_add_u64 v[184:185], v[18:19], 0, v[182:183]
	global_load_dwordx4 v[190:193], v[184:185], off
	v_readlane_b32 s61, v254, 46
	v_readlane_b32 s62, v254, 47
	v_readlane_b32 s63, v254, 48
	v_readlane_b32 s64, v254, 49
	v_readlane_b32 s65, v254, 50
	v_readlane_b32 s70, v254, 55
	v_readlane_b32 s71, v254, 56
	v_readlane_b32 s72, v254, 57
	v_readlane_b32 s73, v254, 58
	v_readlane_b32 s74, v254, 59
	v_readlane_b32 s75, v254, 60
	v_pk_mul_f32 v[16:17], v[30:31], v[16:17]
	v_pk_mul_f32 v[14:15], v[28:29], v[14:15]
	s_cbranch_vccnz .LBB0_360
	v_lshlrev_b32_e32 v0, 1, v140
	v_lshl_add_u64 v[28:29], v[20:21], 0, v[0:1]
	v_lshl_add_u64 v[30:31], v[18:19], 0, v[0:1]
	s_waitcnt vmcnt(0)
	v_mov_b64_e32 v[28:29], v[186:187]
	v_pk_mul_f32 v[34:35], v[14:15], v[28:29]
	v_mov_b64_e32 v[30:31], v[190:191]
	v_pk_mul_f32 v[32:33], v[14:15], v[30:31] op_sel:[1,0] op_sel_hi:[0,0]
	v_mov_b32_e32 v30, v29
	v_mul_f32_e32 v0, v17, v31
	v_pk_fma_f32 v[14:15], v[14:15], v[28:29], v[32:33] op_sel_hi:[1,0,1]
	v_pk_fma_f32 v[36:37], v[16:17], v[30:31], v[0:1] op_sel_hi:[1,1,0] neg_lo:[0,0,1] neg_hi:[0,0,1]
	v_mov_b32_e32 v28, v31
	v_mul_f32_e32 v0, v17, v29
	v_pk_fma_f32 v[28:29], v[16:17], v[28:29], v[0:1] op_sel_hi:[1,1,0]
	v_sub_f32_e32 v14, v34, v32
	v_mov_b32_e32 v16, v36
	v_mov_b32_e32 v17, v28

; template <int EPI>
; DI void gemm_epilogue(const Params& p, int layer, f32x4 (&acc)[2][2][4][2], int brow, int bcol, int pn, int wr, int wc,
;                       int fr, int fq, char* smem, int ksplit = -1) {
;     ...
;             if (normed) {
;               float tot = xch[rl * 8 + bj * 4 + wc] + xch[rl * 8 + bj * 4 + (wc ^ 1)];
;               rs = __builtin_amdgcn_rsqf(tot * (1.f / 64.f) + EPSN);
;             }
;             u32x4 o;
; #pragma unroll
;             for (int n = 0; n < 2; ++n) {
;               const int cih = (wc & 1) * 32 + fq * 8 + n * 4;
;               f32x4 v = acc[ai][bj][m][n];
;               if (normed) {
;                 f32x4 g = *(const f32x4*)(gq + cih);
;                 v = v * rs * g;
;                 if (latent) {
;                   const float2 cs = *(const float2*)(p.ropec + spos * 32 + (cih >> 1));
;                   const float2 sn = *(const float2*)(p.ropes + spos * 32 + (cih >> 1));
;                   f32x4 r;
;                   r[0] = v[0] * cs.x - v[1] * sn.x;
;                   r[1] = v[0] * sn.x + v[1] * cs.x;
;                   r[2] = v[2] * cs.y - v[3] * sn.y;
;                   r[3] = v[2] * sn.y + v[3] * cs.y;
;                   v = r;
;                 }
;                 if (pn == 9) v = v * 0.125f;
;               }
;               o[2 * n] = pk_bf16(v[0], v[1]);
;               o[2 * n + 1] = pk_bf16(v[2], v[3]);
;             }
;             *(u32x4*)(Z + (size_t)row * ZW + bcol + bj * 128 + wc * 32 + fq * 8) = o;
.LBB0_362:
	v_pk_mul_f32 v[22:23], v[14:15], s[54:55] op_sel_hi:[1,0]
	v_pk_mul_f32 v[28:29], v[16:17], s[54:55] op_sel_hi:[1,0]
	v_cndmask_b32_e64 v15, v15, v23, s[0:1]
	v_cndmask_b32_e64 v0, v17, v29, s[0:1]
	v_cndmask_b32_e64 v16, v16, v28, s[0:1]
	v_cndmask_b32_e64 v14, v14, v22, s[0:1]
	v_cvt_pk_bf16_f32 v14, v14, v15
	v_cvt_pk_bf16_f32 v15, v16, v0
	v_pk_mul_f32 v[16:17], v[10:11], s[54:55] op_sel_hi:[1,0]
	v_pk_mul_f32 v[22:23], v[12:13], s[54:55] op_sel_hi:[1,0]
	v_cndmask_b32_e64 v11, v11, v17, s[0:1]
	v_cndmask_b32_e64 v0, v13, v23, s[0:1]
	v_cndmask_b32_e64 v12, v12, v22, s[0:1]
	v_cndmask_b32_e64 v10, v10, v16, s[0:1]
	v_mad_i64_i32 v[156:157], s[2:3], v26, s79, v[122:123]
	v_cvt_pk_bf16_f32 v16, v10, v11
	v_cvt_pk_bf16_f32 v17, v12, v0
	s_and_b64 vcc, exec, s[42:43]
	v_mov_b32_e32 v10, 1.0
	v_lshl_add_u64 v[156:157], v[156:157], 0, v[194:195]
	ds_bpermute_b32 v14, v196, v14
	ds_bpermute_b32 v15, v196, v15
	ds_bpermute_b32 v16, v196, v16
	ds_bpermute_b32 v17, v196, v17
	s_waitcnt lgkmcnt(0)
	global_store_dwordx4 v[156:157], v[14:17], off
	s_cbranch_vccnz .LBB0_365
	v_xor_b32_e32 v0, 5, v25
	v_lshl_add_u32 v0, v0, 2, 0
	v_add_u32_e32 v0, 0x20000, v0
	ds_read_b32 v10, v24 offset:16
	ds_read_b32 v0, v0
	s_waitcnt lgkmcnt(0)
	v_add_f32_e32 v0, v10, v0
	v_fmamk_f32 v0, v0, 0x3c800000, v236
	v_rsq_f32_e32 v10, v0
	s_and_b64 vcc, exec, s[42:43]
	v_mov_b32_e32 v11, v10
	s_cbranch_vccz .LBB0_366

; template <int EPI>
; DI void gemm_epilogue(const Params& p, int layer, f32x4 (&acc)[2][2][4][2], int brow, int bcol, int pn, int wr, int wc,
;                       int fr, int fq, char* smem, int ksplit = -1) {
;     ...
;               o[2 * n] = pk_bf16(v[0], v[1]);
;               o[2 * n + 1] = pk_bf16(v[2], v[3]);
;             }
;             *(u32x4*)(Z + (size_t)row * ZW + bcol + bj * 128 + wc * 32 + fq * 8) = o;
.LBB0_373:
	v_cvt_pk_bf16_f32 v132, v134, v135
	v_cvt_pk_bf16_f32 v133, v136, v137
	s_andn2_b64 vcc, exec, s[36:37]
	s_mov_b64 s[0:1], -1
	ds_bpermute_b32 v130, v196, v130
	ds_bpermute_b32 v131, v196, v131
	ds_bpermute_b32 v132, v196, v132
	ds_bpermute_b32 v133, v196, v133
	s_waitcnt lgkmcnt(0)
	global_store_dwordx4 v[156:157], v[130:133], off offset:256
